# prep: bias partial-sum loop loads batched (bit-identical order)
# speedup vs baseline: 1.0265x; 1.0035x over previous
; DEVI void phase_prep(const Params& p, int L, char* smem) {
;     ...
;       int n = tid & 127, half = tid >> 7;
;       float s = 0.f;
; #pragma unroll 8
;       for (int k = half * 32; k < half * 32 + 32; ++k) s += pe[k] * w1[(long)k * 128 + n];
.LBB0_2184:
	global_load_dwordx4 v[14:17], v[6:7], off offset:-12
	global_load_dwordx4 v[18:21], v[6:7], off offset:-28
	global_load_dword v236, v[4:5], off
	global_load_dword v237, v[4:5], off offset:512
	global_load_dword v238, v[4:5], off offset:1024
	global_load_dword v239, v[4:5], off offset:1536
	v_add_u32_e32 v244, 5, v8
	v_ashrrev_i32_e32 v245, 31, v244
	v_lshlrev_b64 v[244:245], 9, v[244:245]
	v_lshl_add_u64 v[244:245], v[2:3], 0, v[244:245]
	global_load_dword v240, v[244:245], off
	v_add_u32_e32 v244, 6, v8
	v_ashrrev_i32_e32 v245, 31, v244
	v_lshlrev_b64 v[244:245], 9, v[244:245]
	v_lshl_add_u64 v[244:245], v[2:3], 0, v[244:245]
	global_load_dword v241, v[244:245], off
	v_add_u32_e32 v244, 7, v8
	v_ashrrev_i32_e32 v245, 31, v244
	v_lshlrev_b64 v[244:245], 9, v[244:245]
	v_lshl_add_u64 v[244:245], v[2:3], 0, v[244:245]
	global_load_dword v242, v[244:245], off
	global_load_dword v243, v[4:5], off offset:3584
	s_mov_b64 s[6:7], 0x1000
	v_lshl_add_u64 v[6:7], v[6:7], 0, 32
	v_add_u32_e32 v8, 8, v8
	v_cmp_ge_i32_e32 vcc, v8, v11
	s_or_b64 s[14:15], vcc, s[14:15]
	v_lshl_add_u64 v[4:5], v[4:5], 0, s[6:7]
	s_waitcnt vmcnt(0)
	v_fmac_f32_e32 v12, v18, v236
	v_fmac_f32_e32 v12, v19, v237
	v_fmac_f32_e32 v12, v20, v238
	v_fmac_f32_e32 v12, v21, v239
	v_fmac_f32_e32 v12, v14, v240
	v_fmac_f32_e32 v12, v15, v241
	v_fmac_f32_e32 v12, v16, v242
	v_fmac_f32_e32 v12, v17, v243
	s_andn2_b64 exec, exec, s[14:15]
	s_cbranch_execnz .LBB0_2184
	s_or_b64 exec, exec, s[14:15]
